# merge unit header waits only for the tail's DMA (vmcnt(8)); W_o/FFN2 vmcnt(4)
# speedup vs baseline: 1.0095x; 1.0091x over previous
.LBB0_236:
	v_mov_b32_e32 v67, v169
	s_mov_b32 s4, s11
	v_lshrrev_b32_e32 v69, 4, v67
	v_ashrrev_i32_e32 v71, 3, v67
	v_lshrrev_b32_e32 v77, 1, v67
	v_and_b32_e32 v80, 4, v69
	v_and_b32_e32 v81, 3, v71
	v_and_b32_e32 v73, 7, v67
	v_xor_b32_e32 v75, v71, v67
	v_and_b32_e32 v77, 16, v77
	v_and_b32_e32 v79, 8, v69
	v_or_b32_e32 v82, v80, v81
	v_lshlrev_b32_e32 v75, 4, v75
	v_or3_b32 v77, v77, v79, v82
	v_bitop3_b32 v79, v80, v73, v81 bitop3:0x36
	v_lshlrev_b32_e32 v71, 7, v71
	v_lshlrev_b32_e32 v79, 4, v79
	v_and_or_b32 v115, v75, s24, v71
	v_lshl_or_b32 v114, v77, 7, v79
	v_lshlrev_b32_e32 v34, 7, v67
	v_and_b32_e32 v35, 0x780, v34
	v_and_b32_e32 v120, 0x2780, v34
	v_bitop3_b32 v34, v69, v73, 3 bitop3:0x6c
	v_bfe_u32 v77, v67, 4, 2
	v_lshlrev_b32_e32 v121, 4, v34
	v_lshlrev_b32_e32 v34, 6, v67
	v_mov_b32_e32 v75, v1
	v_and_or_b32 v122, v34, s30, v35
	v_bitop3_b32 v34, v77, v73, 4 bitop3:0x36
	v_mov_b32_e32 v79, v1
	v_mov_b32_e32 v71, v1
	v_mov_b32_e32 v77, v1
	v_mov_b32_e32 v69, v1
	v_lshl_add_u64 v[108:109], v[74:75], 1, s[28:29]
	v_mov_b32_e32 v67, v1
	v_mov_b32_e32 v73, v1
	v_mov_b32_e32 v74, 0
	s_mov_b32 s9, s10
	s_mov_b32 s2, s15
	s_mov_b32 s25, s14
	v_lshlrev_b32_e32 v123, 4, v34
	v_lshl_add_u64 v[98:99], v[0:1], 1, s[34:35]
	v_lshl_add_u64 v[100:101], v[78:79], 1, s[28:29]
	v_lshl_add_u64 v[102:103], v[70:71], 1, s[34:35]
	v_lshl_add_u64 v[104:105], v[76:77], 1, s[28:29]
	v_lshl_add_u64 v[106:107], v[68:69], 1, s[34:35]
	v_lshl_add_u64 v[110:111], v[66:67], 1, s[34:35]
	v_lshl_add_u64 v[112:113], v[72:73], 1, s[28:29]
	v_lshrrev_b32_e32 v223, 6, v169
	v_lshlrev_b32_e32 v223, 10, v223
	s_lshl_b32 s99, s101, 1
	v_readfirstlane_b32 s100, v223
	v_lshrrev_b32_e32 v222, 3, v169
	v_and_b32_e32 v224, 3, v222
	v_bfe_u32 v223, v222, 4, 1
	v_lshl_or_b32 v224, v223, 2, v224
	v_bfe_u32 v223, v222, 2, 1
	v_lshl_or_b32 v224, v223, 3, v224
	v_bfe_u32 v223, v222, 3, 1
	v_lshl_or_b32 v224, v223, 4, v224
	v_sub_u32_e32 v224, v224, v222
	v_and_b32_e32 v222, 7, v222
	v_mul_i32_i24_e32 v224, s99, v224
	v_lshlrev_b32_e32 v222, 4, v222
	v_ashrrev_i32_e32 v225, 31, v224
	v_xor_b32_e32 v98, v98, v222
	v_lshl_add_u64 v[100:101], v[100:101], 0, v[224:225]
	v_xor_b32_e32 v100, v100, v222
	v_xor_b32_e32 v102, v102, v222
	v_lshl_add_u64 v[104:105], v[104:105], 0, v[224:225]
	v_xor_b32_e32 v104, v104, v222
	v_xor_b32_e32 v106, v106, v222
	v_lshl_add_u64 v[108:109], v[108:109], 0, v[224:225]
	v_xor_b32_e32 v108, v108, v222
	v_xor_b32_e32 v110, v110, v222
	v_lshl_add_u64 v[112:113], v[112:113], 0, v[224:225]
	v_xor_b32_e32 v112, v112, v222
	s_mov_b64 s[28:29], 0
	s_mov_b32 s5, 0
	v_mov_b32_e32 v75, v74
	v_mov_b32_e32 v76, v74
	v_mov_b32_e32 v77, v74
	v_mov_b32_e32 v62, v74
	v_mov_b32_e32 v63, v74
	v_mov_b32_e32 v64, v74
	v_mov_b32_e32 v65, v74
	v_mov_b32_e32 v66, v74
	v_mov_b32_e32 v67, v74
	v_mov_b32_e32 v68, v74
	v_mov_b32_e32 v69, v74
	v_mov_b32_e32 v58, v74
	v_mov_b32_e32 v59, v74
	v_mov_b32_e32 v60, v74
	v_mov_b32_e32 v61, v74
	v_mov_b32_e32 v70, v74
	v_mov_b32_e32 v71, v74
	v_mov_b32_e32 v72, v74
	v_mov_b32_e32 v73, v74
	v_mov_b32_e32 v54, v74
	v_mov_b32_e32 v55, v74
	v_mov_b32_e32 v56, v74
	v_mov_b32_e32 v57, v74
	v_mov_b32_e32 v78, v74
	v_mov_b32_e32 v79, v74
	v_mov_b32_e32 v80, v74
	v_mov_b32_e32 v81, v74
	v_mov_b32_e32 v50, v74
	v_mov_b32_e32 v51, v74
	v_mov_b32_e32 v52, v74
	v_mov_b32_e32 v53, v74
	v_mov_b32_e32 v82, v74
	v_mov_b32_e32 v83, v74
	v_mov_b32_e32 v84, v74
	v_mov_b32_e32 v85, v74
	v_mov_b32_e32 v46, v74
	v_mov_b32_e32 v47, v74
	v_mov_b32_e32 v48, v74
	v_mov_b32_e32 v49, v74
	v_mov_b32_e32 v86, v74
	v_mov_b32_e32 v87, v74
	v_mov_b32_e32 v88, v74
	v_mov_b32_e32 v89, v74
	v_mov_b32_e32 v42, v74
	v_mov_b32_e32 v43, v74
	v_mov_b32_e32 v44, v74
	v_mov_b32_e32 v45, v74
	v_mov_b32_e32 v90, v74
	v_mov_b32_e32 v91, v74
	v_mov_b32_e32 v92, v74
	v_mov_b32_e32 v93, v74
	v_mov_b32_e32 v38, v74
	v_mov_b32_e32 v39, v74
	v_mov_b32_e32 v40, v74
	v_mov_b32_e32 v41, v74
	v_mov_b32_e32 v94, v74
	v_mov_b32_e32 v95, v74
	v_mov_b32_e32 v96, v74
	v_mov_b32_e32 v97, v74
	v_mov_b32_e32 v34, v74
	v_mov_b32_e32 v35, v74
	v_mov_b32_e32 v36, v74
	v_mov_b32_e32 v37, v74
	s_waitcnt vmcnt(8)
	s_waitcnt lgkmcnt(0)
	s_barrier
